# fastdiv + attention pass prologue: third K/V tile loads issued before waiting for the second tile (3 of 4 pass instantiations)
# baseline (speedup 1.0000x reference)
; #define GAS __attribute__((address_space(1)))
; __device__ __forceinline__ float bf2f(unsigned short b) { return __uint_as_float(((unsigned)b) << 16); }
; template <bool GRPB> __device__ __forceinline__ void attn_pass(const float mbK, const float bmax2, const int pass, float* __restrict__ scr, bf16* __restrict__ mixrow, const float lam, const float* __restrict__ gsub, const float one_m_li, ...
;     ...
;   const float cL = __uint_as_float(__builtin_amdgcn_readfirstlane(__float_as_uint(tb2[0]))), cR = __uint_as_float(__builtin_amdgcn_readfirstlane(__float_as_uint(tb2[384])));
;   const int qw = __builtin_amdgcn_readfirstlane(q0seq + wid * 32), qpos = qw + r32;
;   float m_reg, l_reg = 0; bf16x8 qr[4]; f32x16 o[4];
; #pragma unroll
;   for (int d = 0; d < 4; ++d) o[d] = f32x16{};
;   const bf16* Qw = Qb + (long)(wid * 32 + r32) * LDK + hi * 8;
; #pragma unroll
;   for (int d0 = 0; d0 < 4; ++d0) qr[d0] = *(const GAS bf16x8*)(Qw + d0 * 16);
;   { float qs = 0.f;
; #pragma unroll
;     for (int d0 = 0; d0 < 4; ++d0)
; #pragma unroll
;       for (int j = 0; j < 8; ++j) { const float v = bf2f((unsigned short)qr[d0][j]); qs = fmaf(v, v, qs); }
;     { auto rr = __builtin_amdgcn_permlane32_swap(__float_as_uint(qs), __float_as_uint(qs), false, false); qs = __uint_as_float(rr[0]) + __uint_as_float(rr[1]); }
;     m_reg = __builtin_sqrtf(qs) * mbK + bmax2 + 0.25f; }
; __device__ __forceinline__ void attn_phase(const Params& p, int e, char* lds) {
;     ...
;     const unsigned* kmx = (const unsigned*)(p.ws + WS_KMX) + e * 128 + b * 8 + h * 2;
;     const float mbK0 = __uint_as_float(__builtin_amdgcn_readfirstlane(__float_as_uint(C1 * 1.01f * __builtin_sqrtf(2.0f * __uint_as_float(kmx[0])))));
;     const float mbK1 = __uint_as_float(__builtin_amdgcn_readfirstlane(__float_as_uint(C1 * 1.01f * __builtin_sqrtf(2.0f * __uint_as_float(kmx[1])))));
;     bmax2 = __uint_as_float(__builtin_amdgcn_readfirstlane(__float_as_uint(bmax2)));
;     if (__builtin_amdgcn_readfirstlane(wid) & 1) {
.LBB0_295:
	s_lshl_b32 s0, s59, 8
	s_ashr_i32 s48, s59, 6
	s_and_b32 s39, s0, 0xf00
	s_ashr_i32 s49, s48, 31
	s_lshl_b32 s0, s48, 3
	s_lshl_b64 s[46:47], s[48:49], 12
	s_ashr_i32 s1, s0, 31
	s_or_b32 s46, s46, s39
	s_lshl_b64 s[0:1], s[0:1], 2
	s_add_u32 s0, s35, s0
	s_addc_u32 s1, s56, s1
	s_lshl_b32 s2, s44, 3
	s_add_u32 s0, s0, s2
	s_addc_u32 s1, s1, 0
	v_mov_b64_e32 v[2:3], s[0:1]
	flat_load_dwordx2 v[2:3], v[2:3]
	s_mov_b32 s2, 0xf800000
	v_mov_b32_e32 v6, 0x3fba82f9
	v_readfirstlane_b32 s45, v0
	v_lshrrev_b32_e32 v0, 6, v232
	s_mov_b32 s10, 0xf800000
	v_mov_b32_e32 v198, 0x260
	s_waitcnt vmcnt(0) lgkmcnt(0)
	v_add_f32_e32 v1, v2, v2
	v_cmp_gt_f32_e32 vcc, s2, v1
	v_mul_f32_e32 v2, 0x4f800000, v1
	s_nop 0
	v_cndmask_b32_e32 v1, v1, v2, vcc
	v_sqrt_f32_e32 v2, v1
	s_nop 0
	v_add_u32_e32 v4, -1, v2
	v_fma_f32 v5, -v4, v2, v1
	v_cmp_ge_f32_e64 s[0:1], 0, v5
	v_add_u32_e32 v5, 1, v2
	s_nop 0
	v_cndmask_b32_e64 v4, v2, v4, s[0:1]
	v_fma_f32 v2, -v5, v2, v1
	v_cmp_lt_f32_e64 s[0:1], 0, v2
	s_nop 1
	v_cndmask_b32_e64 v2, v4, v5, s[0:1]
	v_mul_f32_e32 v4, 0x37800000, v2
	v_mov_b32_e32 v5, 0x260
	v_cndmask_b32_e32 v2, v2, v4, vcc
	v_cmp_class_f32_e32 vcc, v1, v5
	s_nop 1
	v_cndmask_b32_e32 v1, v2, v1, vcc
	s_nop 0
	v_readfirstlane_b32 s0, v1
	v_add_f32_e32 v1, v3, v3
	v_cmp_gt_f32_e32 vcc, s2, v1
	v_mul_f32_e32 v2, 0x4f800000, v1
	v_mul_f32_e32 v216, s0, v6
	v_cndmask_b32_e32 v1, v1, v2, vcc
	v_sqrt_f32_e32 v2, v1
	s_nop 0
	v_add_u32_e32 v3, -1, v2
	v_fma_f32 v4, -v3, v2, v1
	v_cmp_ge_f32_e64 s[0:1], 0, v4
	v_add_u32_e32 v4, 1, v2
	s_nop 0
	v_cndmask_b32_e64 v3, v2, v3, s[0:1]
	v_fma_f32 v2, -v4, v2, v1
	v_cmp_lt_f32_e64 s[0:1], 0, v2
	s_nop 1
	v_cndmask_b32_e64 v2, v3, v4, s[0:1]
	v_mul_f32_e32 v3, 0x37800000, v2
	v_cndmask_b32_e32 v2, v2, v3, vcc
	v_cmp_class_f32_e32 vcc, v1, v5
	s_nop 1
	v_cndmask_b32_e32 v1, v2, v1, vcc
	s_nop 0
	v_readfirstlane_b32 s0, v1
	s_nop 1
	v_mul_f32_e32 v214, s0, v6
	v_readfirstlane_b32 s0, v0
	s_bitcmp1_b32 s0, 0
	s_cselect_b64 s[20:21], -1, 0
	s_lshl_b64 s[0:1], s[46:47], 13
	s_add_u32 s0, s30, s0
	s_addc_u32 s1, s31, s1
	s_lshl_b32 s2, s44, 8
	s_add_u32 s52, s0, s2
	s_addc_u32 s53, s1, 0
	s_lshl_b64 s[48:49], s[48:49], 25
	s_add_u32 s0, s30, s48
	s_addc_u32 s1, s31, s49
	s_add_u32 s50, s0, s2
	s_addc_u32 s51, s1, 0
	s_mov_b64 s[0:1], -1
	s_and_b64 vcc, exec, s[20:21]
	s_cbranch_vccz .LBB0_347
	v_readlane_b32 s0, v254, 39
	v_mov_b32_e32 v146, v232
	v_mov_b32_e32 v201, v144
	v_mov_b32_e32 v0, s0
	ds_read_b32 v0, v0
	v_readlane_b32 s0, v254, 40
	v_lshrrev_b32_e32 v2, 1, v146
	v_and_b32_e32 v200, 16, v2
	v_lshlrev_b32_e32 v8, 4, v146
	s_waitcnt lgkmcnt(0)
	v_readfirstlane_b32 s61, v0
	v_mov_b32_e32 v0, s0
	ds_read_b32 v0, v0
	s_movk_i32 s0, 0xffe0
	v_and_b32_e32 v9, 48, v8
	v_ashrrev_i32_e32 v12, 3, v146
	v_ashrrev_i32_e32 v13, 31, v12
	s_waitcnt lgkmcnt(0)
	v_readfirstlane_b32 s62, v0
	v_ashrrev_i32_e32 v0, 1, v146
	v_and_b32_e32 v1, 0xffffffe0, v0
	v_add_u32_e32 v1, s39, v1
	v_bfi_b32 v0, s0, v0, v146
	v_readfirstlane_b32 s63, v1
	v_ashrrev_i32_e32 v1, 31, v0
	v_lshlrev_b64 v[0:1], 13, v[0:1]
	v_lshl_add_u64 v[0:1], s[52:53], 0, v[0:1]
	v_lshl_add_u64 v[0:1], v[0:1], 0, v[200:201]
	global_load_dwordx4 v[164:167], v[0:1], off
	global_load_dwordx4 v[160:163], v[0:1], off offset:32
	global_load_dwordx4 v[156:159], v[0:1], off offset:64
	global_load_dwordx4 v[152:155], v[0:1], off offset:96
	s_barrier
	v_lshlrev_b64 v[52:53], 13, v[12:13]
	v_mov_b32_e32 v11, v144
	v_and_b32_e32 v147, 31, v146
	v_add_u32_e32 v215, s63, v147
	s_waitcnt vmcnt(3)
	v_lshlrev_b32_e32 v0, 16, v164
	v_fma_f32 v0, v0, v0, 0
	v_and_b32_e32 v1, 0xffff0000, v164
	v_fmac_f32_e32 v0, v1, v1
	v_lshlrev_b32_e32 v1, 16, v165
	v_fmac_f32_e32 v0, v1, v1
	v_and_b32_e32 v1, 0xffff0000, v165
	v_fmac_f32_e32 v0, v1, v1
	v_lshlrev_b32_e32 v1, 16, v166
	v_fmac_f32_e32 v0, v1, v1
	v_and_b32_e32 v1, 0xffff0000, v166
	v_fmac_f32_e32 v0, v1, v1
	v_lshlrev_b32_e32 v1, 16, v167
	v_fmac_f32_e32 v0, v1, v1
	v_and_b32_e32 v1, 0xffff0000, v167
	v_fmac_f32_e32 v0, v1, v1
	s_waitcnt vmcnt(2)
	v_lshlrev_b32_e32 v1, 16, v160
	v_fmac_f32_e32 v0, v1, v1
	v_and_b32_e32 v1, 0xffff0000, v160
	v_fmac_f32_e32 v0, v1, v1
	v_lshlrev_b32_e32 v1, 16, v161
	v_fmac_f32_e32 v0, v1, v1
	v_and_b32_e32 v1, 0xffff0000, v161
	v_fmac_f32_e32 v0, v1, v1
	v_lshlrev_b32_e32 v1, 16, v162
	v_fmac_f32_e32 v0, v1, v1
	v_and_b32_e32 v1, 0xffff0000, v162
	v_fmac_f32_e32 v0, v1, v1
	v_lshlrev_b32_e32 v1, 16, v163
	v_fmac_f32_e32 v0, v1, v1
	v_and_b32_e32 v1, 0xffff0000, v163
	v_fmac_f32_e32 v0, v1, v1
	s_waitcnt vmcnt(1)
	v_lshlrev_b32_e32 v1, 16, v156
	v_fmac_f32_e32 v0, v1, v1
	v_and_b32_e32 v1, 0xffff0000, v156
	v_fmac_f32_e32 v0, v1, v1
	v_lshlrev_b32_e32 v1, 16, v157
	v_fmac_f32_e32 v0, v1, v1
	v_and_b32_e32 v1, 0xffff0000, v157
	v_fmac_f32_e32 v0, v1, v1
	v_lshlrev_b32_e32 v1, 16, v158
	v_fmac_f32_e32 v0, v1, v1
	v_and_b32_e32 v1, 0xffff0000, v158
	v_fmac_f32_e32 v0, v1, v1
	v_lshlrev_b32_e32 v1, 16, v159
	v_fmac_f32_e32 v0, v1, v1
	v_and_b32_e32 v1, 0xffff0000, v159
	v_fmac_f32_e32 v0, v1, v1
	s_waitcnt vmcnt(0)
; __device__ __forceinline__ float bf2f(unsigned short b) { return __uint_as_float(((unsigned)b) << 16); }
; __device__ __forceinline__ int v_st(int k, int c) { const int kk = (k & ~0xC) | ((k & 4) << 1) | ((k & 8) >> 1); return ((kk >> 3) * 4 + (c >> 5)) * 512 + ((kk & 7) * 32 + (c & 31)) * 2; }
; __device__ __forceinline__ int v_rd_base(int lane) { return ((lane & 3) << 3) | (((lane >> 2) & 3) << 6) | (((lane >> 4) & 1) << 5) | (((lane >> 5) & 1) << 8); }
; #define SLOAD(i, k0) do { sr_[i].vs0 = *(const GAS bf16x8*)(&Vh[(long)((k0) + sr) * LDK + sc]); sr_[i].vs1 = *(const GAS bf16x8*)(&Vh[(long)((k0) + 32 + sr) * LDK + sc]); \
;     sr_[i].ks0 = *(const GAS bf16x8*)(&Kh[(long)((k0) + kr) * LDK + kc]); } while (0)
; #define SWRITE(b, i) do { *(bf16x8*)(V_lds + (b) * SHM_V + vst0) = sr_[i].vs0; *(bf16x8*)(V_lds + (b) * SHM_V + vst1) = sr_[i].vs1; \
;     *(bf16x8*)(K_lds + (b) * SHM_K + kst) = sr_[i].ks0; } while (0)
; template <bool GRPB> __device__ __forceinline__ void attn_pass(const float mbK, const float bmax2, const int pass, float* __restrict__ scr, bf16* __restrict__ mixrow, const float lam, const float* __restrict__ gsub, const float one_m_li, ...
;     ...
;   { float qs = 0.f;
; #pragma unroll
;     for (int d0 = 0; d0 < 4; ++d0)
; #pragma unroll
;       for (int j = 0; j < 8; ++j) { const float v = bf2f((unsigned short)qr[d0][j]); qs = fmaf(v, v, qs); }
;     { auto rr = __builtin_amdgcn_permlane32_swap(__float_as_uint(qs), __float_as_uint(qs), false, false); qs = __uint_as_float(rr[0]) + __uint_as_float(rr[1]); }
;     m_reg = __builtin_sqrtf(qs) * mbK + bmax2 + 0.25f; }
;   const int sr = tid >> 4, sc = (tid & 15) * 8, vst0 = v_st(sr, sc), vst1 = v_st(32 + sr, sc);
;   const int kr = tid >> 3, kc = (tid & 7) * 8, kst = KSWZ64(kr, kc * 2);
;   const int vb0 = (int)(uintptr_t)V_lds + v_rd_base(lane);
;   struct { bf16x8 vs0, vs1, ks0; } sr_[2];
;     ...
;   f32x16 pA0, pA1, pB0, pB1; float mnA, mnB, alA, alB; bf16x8 pa0, pa1, pa2, pa3; constexpr int NT = SEQ / KVBLK;
;   __syncthreads();
;   SLOAD(0, 0); SLOAD(1, KVBLK); asm volatile("s_waitcnt vmcnt(0)" ::: "memory"); SWRITE(0, 0); SWRITE(1, 1);
;   SLOAD(0, 2 * KVBLK); asm volatile("s_waitcnt vmcnt(0)" ::: "memory"); SWRITE(2, 0); __syncthreads();
	v_lshlrev_b32_e32 v1, 16, v152
	v_fmac_f32_e32 v0, v1, v1
	v_and_b32_e32 v1, 0xffff0000, v152
	v_fmac_f32_e32 v0, v1, v1
	v_lshlrev_b32_e32 v1, 16, v153
	v_fmac_f32_e32 v0, v1, v1
	v_and_b32_e32 v1, 0xffff0000, v153
	v_fmac_f32_e32 v0, v1, v1
	v_lshlrev_b32_e32 v1, 16, v154
	v_fmac_f32_e32 v0, v1, v1
	v_and_b32_e32 v1, 0xffff0000, v154
	v_fmac_f32_e32 v0, v1, v1
	v_lshlrev_b32_e32 v1, 16, v155
	v_fmac_f32_e32 v0, v1, v1
	v_and_b32_e32 v1, 0xffff0000, v155
	v_fmac_f32_e32 v0, v1, v1
	v_mov_b32_e32 v1, v0
	s_nop 1
	v_permlane32_swap_b32_e32 v0, v1
	v_add_f32_e32 v0, v0, v1
	v_cmp_gt_f32_e32 vcc, s10, v0
	v_mul_f32_e32 v1, 0x4f800000, v0
	s_nop 0
	v_cndmask_b32_e32 v0, v0, v1, vcc
	v_sqrt_f32_e32 v1, v0
	s_nop 0
	v_add_u32_e32 v2, -1, v1
	v_fma_f32 v3, -v2, v1, v0
	v_cmp_ge_f32_e64 s[0:1], 0, v3
	v_add_u32_e32 v3, 1, v1
	s_nop 0
	v_cndmask_b32_e64 v2, v1, v2, s[0:1]
	v_fma_f32 v1, -v3, v1, v0
	v_cmp_lt_f32_e64 s[0:1], 0, v1
	s_nop 1
	v_cndmask_b32_e64 v1, v2, v3, s[0:1]
	v_mul_f32_e32 v2, 0x37800000, v1
	v_cndmask_b32_e32 v1, v1, v2, vcc
	v_ashrrev_i32_e32 v2, 4, v146
	v_cmp_class_f32_e32 vcc, v0, v198
	v_and_b32_e32 v3, 0xfffff0, v2
	v_lshlrev_b32_e32 v5, 1, v2
	v_cndmask_b32_e32 v0, v1, v0, vcc
	v_lshlrev_b32_e32 v1, 3, v146
	v_and_or_b32 v3, v5, 8, v3
	v_lshrrev_b32_e32 v5, 1, v2
	v_lshrrev_b32_e32 v3, 1, v3
	v_bfe_u32 v7, v1, 5, 2
	v_and_b32_e32 v6, 3, v2
	v_or_b32_e32 v3, v3, v7
	v_and_or_b32 v5, v5, 4, v6
	v_lshlrev_b32_e32 v3, 9, v3
	v_lshlrev_b32_e32 v5, 6, v5
	v_add_u32_e32 v6, 32, v2
	v_or3_b32 v201, v3, v5, v9
	v_and_b32_e32 v3, 0xfffff0, v6
	v_lshlrev_b32_e32 v10, 1, v6
	v_and_or_b32 v3, v10, 8, v3
	v_lshrrev_b32_e32 v3, 1, v3
	v_or_b32_e32 v3, v3, v7
	v_lshlrev_b32_e32 v3, 9, v3
	v_or3_b32 v217, v3, v5, v9
	v_lshlrev_b32_e32 v3, 7, v12
	v_and_b32_e32 v10, 0x70, v8
	v_and_b32_e32 v5, 0x70, v146
	v_bitop3_b32 v218, v10, v3, v5 bitop3:0xde
	v_ashrrev_i32_e32 v3, 31, v2
	v_and_b32_e32 v4, 0x78, v1
	v_lshlrev_b64 v[50:51], 13, v[2:3]
	v_lshl_add_u64 v[2:3], s[50:51], 0, v[50:51]
	v_lshlrev_b32_e32 v8, 1, v4
	v_mov_b32_e32 v9, v144
	v_ashrrev_i32_e32 v7, 31, v6
	v_lshl_add_u64 v[18:19], v[2:3], 0, v[8:9]
	v_lshlrev_b64 v[6:7], 13, v[6:7]
	global_load_dwordx4 v[2:5], v[18:19], off offset:2048
	v_lshl_add_u64 v[6:7], s[50:51], 0, v[6:7]
	s_mov_b32 s0, 0x80000
	v_lshl_add_u64 v[6:7], v[6:7], 0, v[8:9]
	v_add_co_u32_e32 v14, vcc, s0, v18
	global_load_dwordx4 v[6:9], v[6:7], off offset:2048
	v_lshl_add_u64 v[12:13], s[50:51], 0, v[52:53]
	v_addc_co_u32_e32 v15, vcc, 0, v19, vcc
	s_mov_b32 s1, 0xc0000
	v_lshl_add_u64 v[20:21], v[12:13], 0, v[10:11]
	v_add_co_u32_e32 v22, vcc, s1, v18
	global_load_dwordx4 v[10:13], v[20:21], off offset:1024
	s_nop 0
	v_addc_co_u32_e32 v23, vcc, 0, v19, vcc
	global_load_dwordx4 v[14:17], v[14:15], off offset:2048
	v_add_co_u32_e32 v26, vcc, s0, v20
	global_load_dwordx4 v[22:25], v[22:23], off offset:2048
	s_nop 0
	v_addc_co_u32_e32 v27, vcc, 0, v21, vcc
	global_load_dwordx4 v[26:29], v[26:27], off offset:1024
	v_add_u32_e32 v30, 0, v201
	s_mov_b32 s0, 0x100000
	s_waitcnt vmcnt(3)
	v_add_u32_e32 v31, 0, v217
	s_mov_b32 s1, 0x140000
	v_add_u32_e32 v222, 0, v218
	v_and_b32_e32 v1, 0x70, v1
	v_fma_f32 v0, v216, v0, s45
	v_add_f32_e32 v0, 0x3e800000, v0
	s_waitcnt vmcnt(5)
	ds_write_b128 v30, v[2:5]
	v_add_co_u32_e32 v2, vcc, s0, v18
	s_waitcnt vmcnt(4)
	ds_write_b128 v31, v[6:9]
	v_addc_co_u32_e32 v3, vcc, 0, v19, vcc
	v_add_co_u32_e32 v6, vcc, s1, v18
	s_waitcnt vmcnt(3)
	ds_write_b128 v222, v[10:13] offset:49152
	v_addc_co_u32_e32 v7, vcc, 0, v19, vcc
	v_add_co_u32_e32 v10, vcc, s0, v20
	global_load_dwordx4 v[2:5], v[2:3], off offset:2048
	s_nop 0
	v_addc_co_u32_e32 v11, vcc, 0, v21, vcc
	global_load_dwordx4 v[6:9], v[6:7], off offset:2048
	s_nop 0
	global_load_dwordx4 v[10:13], v[10:11], off offset:1024
	s_waitcnt vmcnt(5)
	ds_write_b128 v30, v[14:17] offset:16384
	s_waitcnt vmcnt(4)
	ds_write_b128 v31, v[22:25] offset:16384
	s_waitcnt vmcnt(3)
	ds_write_b128 v222, v[26:29] offset:57344
	s_waitcnt vmcnt(0)
	s_waitcnt vmcnt(2)
	ds_write_b128 v30, v[2:5] offset:32768
	s_waitcnt vmcnt(1)
	ds_write_b128 v31, v[6:9] offset:32768
	v_add_u32_e32 v2, 0x10000, v222
	s_waitcnt vmcnt(0)
	ds_write_b128 v2, v[10:13]
	v_lshlrev_b32_e32 v10, 7, v147
	v_or_b32_e32 v11, 32, v200
	v_bitop3_b32 v227, v11, v10, v1 bitop3:0xde
	v_or_b32_e32 v11, 64, v200
	v_bitop3_b32 v229, v11, v10, v1 bitop3:0xde
	v_or_b32_e32 v11, 0x60, v200
	v_bitop3_b32 v224, v200, v10, v1 bitop3:0xde
	v_bitop3_b32 v230, v11, v10, v1 bitop3:0xde
	v_add_u32_e32 v223, 0, v224
	v_add_u32_e32 v225, 0, v227
	v_add_u32_e32 v226, 0, v229
	v_add_u32_e32 v228, 0, v230
	s_waitcnt lgkmcnt(0)
	s_barrier
; #define SBAR() __builtin_amdgcn_sched_barrier(0)
; __device__ __forceinline__ void partialSM(f32x16& p0, f32x16& p1, float& m_reg, float& mn, float& alpha, int kt0, int qpos, int qw, int hi, const float* tb2, float cL, float cR) {
;   mn = m_reg; alpha = 1.f;
;   const int rel_hi = kt0 + 63 - qw, rel_lo = kt0 - (qw + 31);
;   if (rel_hi <= -91 || rel_lo >= 91) {
;     const float cm = ((rel_hi <= -91) ? cL : cR) - m_reg;
; #pragma unroll
;     for (int r = 0; r < 16; ++r) { p0[r] = fmaf(p0[r], C1, cm); p1[r] = fmaf(p1[r], C1, cm); }
;   } else {
;     const float* tp = tb2 + (kt0 - qpos + 192 + 4 * hi);
; #pragma unroll
;     for (int r4 = 0; r4 < 4; ++r4) {
;       float ta[4], tb[4];
; #pragma unroll
;       for (int i = 0; i < 4; ++i) { ta[i] = tp[8 * r4 + i] - m_reg; tb[i] = tp[32 + 8 * r4 + i] - m_reg; }
; #pragma unroll
;       for (int i = 0; i < 4; ++i) { p0[4 * r4 + i] = fmaf(p0[4 * r4 + i], C1, ta[i]); p1[4 * r4 + i] = fmaf(p1[4 * r4 + i], C1, tb[i]); }
; __device__ __forceinline__ void qkt(f32x16& p0, f32x16& p1, const char* Ks, const bf16x8* qr, int r32, int hi) {
;   bf16x8 ka[4], kb[4];
; #pragma unroll
;   for (int d0 = 0; d0 < 4; ++d0) { const int cb = (d0 * 16 + hi * 8) * 2;
;     ka[d0] = *reinterpret_cast<const bf16x8*>(Ks + KSWZ64(r32, cb)); kb[d0] = *reinterpret_cast<const bf16x8*>(Ks + KSWZ64(32 + r32, cb)); }
;   asm volatile("s_waitcnt lgkmcnt(0)" ::: "memory"); SBAR();
;   p0 = f32x16{}; p1 = f32x16{};
; #pragma unroll
;   for (int d0 = 0; d0 < 4; ++d0) {
;     p0 = __builtin_amdgcn_mfma_f32_32x32x16_bf16(ka[d0], qr[d0], p0, 0, 0, 0);
;     p1 = __builtin_amdgcn_mfma_f32_32x32x16_bf16(kb[d0], qr[d0], p1, 0, 0, 0); }
; }
	ds_read_b128 v[2:5], v223 offset:49152
	ds_read_b128 v[6:9], v223 offset:53248
	ds_read_b128 v[34:37], v225 offset:49152
	ds_read_b128 v[38:41], v225 offset:53248
	ds_read_b128 v[42:45], v226 offset:49152
	ds_read_b128 v[46:49], v226 offset:53248
	ds_read_b128 v[54:57], v228 offset:49152
	ds_read_b128 v[58:61], v228 offset:53248
	s_waitcnt lgkmcnt(0)
	s_waitcnt lgkmcnt(7)
	v_mfma_f32_32x32x16_bf16 v[18:33], v[2:5], v[164:167], 0
	s_add_i32 s2, s63, 0xffffff66
	s_mov_b64 s[0:1], -1
	s_cmp_gt_u32 s2, 0xfffffeec
	s_waitcnt lgkmcnt(6)
	v_mfma_f32_32x32x16_bf16 v[2:17], v[6:9], v[164:167], 0
	s_waitcnt lgkmcnt(5)
	v_mfma_f32_32x32x16_bf16 v[18:33], v[34:37], v[160:163], v[18:33]
	s_waitcnt lgkmcnt(4)
	v_mfma_f32_32x32x16_bf16 v[2:17], v[38:41], v[160:163], v[2:17]
	s_waitcnt lgkmcnt(3)
	v_mfma_f32_32x32x16_bf16 v[18:33], v[42:45], v[156:159], v[18:33]
	s_waitcnt lgkmcnt(2)
	v_mfma_f32_32x32x16_bf16 v[2:17], v[46:49], v[156:159], v[2:17]
	s_waitcnt lgkmcnt(1)
	v_mfma_f32_32x32x16_bf16 v[18:33], v[54:57], v[152:155], v[18:33]
	v_lshlrev_b32_e32 v54, 2, v215
	s_waitcnt lgkmcnt(0)
	v_mfma_f32_32x32x16_bf16 v[2:17], v[58:61], v[152:155], v[2:17]
	s_cbranch_scc0 .LBB0_298
	v_sub_u32_e32 v1, 0, v54
	s_mov_b32 s0, 0x12b00
	v_add3_u32 v1, v1, v200, s0
	ds_read2_b32 v[34:35], v1 offset1:1
	ds_read2_b32 v[56:57], v1 offset0:32 offset1:33
	ds_read2_b32 v[58:59], v1 offset0:34 offset1:35
	ds_read2_b32 v[36:37], v1 offset0:2 offset1:3
	ds_read2_b32 v[38:39], v1 offset0:8 offset1:9
	ds_read2_b32 v[60:61], v1 offset0:40 offset1:41
	ds_read2_b32 v[62:63], v1 offset0:42 offset1:43
	ds_read2_b32 v[40:41], v1 offset0:10 offset1:11
	ds_read2_b32 v[42:43], v1 offset0:16 offset1:17
	ds_read2_b32 v[64:65], v1 offset0:48 offset1:49
	ds_read2_b32 v[66:67], v1 offset0:50 offset1:51
	ds_read2_b32 v[44:45], v1 offset0:18 offset1:19
	ds_read2_b32 v[46:47], v1 offset0:24 offset1:25
	ds_read2_b32 v[48:49], v1 offset0:26 offset1:27
	ds_read2_b32 v[68:69], v1 offset0:58 offset1:59
	ds_read2_b32 v[70:71], v1 offset0:56 offset1:57
	s_waitcnt lgkmcnt(3)
	v_sub_f32_e32 v47, v47, v0
	v_sub_f32_e32 v46, v46, v0
	s_waitcnt lgkmcnt(2)
	v_sub_f32_e32 v49, v49, v0
	v_sub_f32_e32 v48, v48, v0
	v_sub_f32_e32 v43, v43, v0
	v_sub_f32_e32 v42, v42, v0
	v_sub_f32_e32 v45, v45, v0
	v_sub_f32_e32 v44, v44, v0
	v_sub_f32_e32 v39, v39, v0
	v_sub_f32_e32 v38, v38, v0
	v_sub_f32_e32 v41, v41, v0
	v_sub_f32_e32 v40, v40, v0
	v_sub_f32_e32 v35, v35, v0
	v_sub_f32_e32 v34, v34, v0
	v_sub_f32_e32 v37, v37, v0
	v_sub_f32_e32 v36, v36, v0
	s_waitcnt lgkmcnt(0)
	v_sub_f32_e32 v71, v71, v0
	v_sub_f32_e32 v70, v70, v0
	v_sub_f32_e32 v69, v69, v0
	v_sub_f32_e32 v68, v68, v0
	v_sub_f32_e32 v65, v65, v0
	v_sub_f32_e32 v64, v64, v0
	v_sub_f32_e32 v67, v67, v0
	v_sub_f32_e32 v66, v66, v0
	v_sub_f32_e32 v61, v61, v0
	v_sub_f32_e32 v60, v60, v0
	v_sub_f32_e32 v63, v63, v0
	v_sub_f32_e32 v62, v62, v0
	v_sub_f32_e32 v57, v57, v0
	v_sub_f32_e32 v56, v56, v0
	v_sub_f32_e32 v59, v59, v0
	v_sub_f32_e32 v58, v58, v0
	v_pk_fma_f32 v[36:37], v[20:21], s[6:7], v[36:37] op_sel_hi:[1,0,1]
	v_pk_fma_f32 v[34:35], v[18:19], s[6:7], v[34:35] op_sel_hi:[1,0,1]
	v_pk_fma_f32 v[40:41], v[24:25], s[6:7], v[40:41] op_sel_hi:[1,0,1]
	v_pk_fma_f32 v[38:39], v[22:23], s[6:7], v[38:39] op_sel_hi:[1,0,1]
	v_pk_fma_f32 v[44:45], v[28:29], s[6:7], v[44:45] op_sel_hi:[1,0,1]
	v_pk_fma_f32 v[42:43], v[26:27], s[6:7], v[42:43] op_sel_hi:[1,0,1]
	v_pk_fma_f32 v[48:49], v[32:33], s[6:7], v[48:49] op_sel_hi:[1,0,1]
	v_pk_fma_f32 v[46:47], v[30:31], s[6:7], v[46:47] op_sel_hi:[1,0,1]
	v_pk_fma_f32 v[82:83], v[4:5], s[6:7], v[58:59] op_sel_hi:[1,0,1]
	v_pk_fma_f32 v[80:81], v[2:3], s[6:7], v[56:57] op_sel_hi:[1,0,1]
	v_pk_fma_f32 v[86:87], v[8:9], s[6:7], v[62:63] op_sel_hi:[1,0,1]
	v_pk_fma_f32 v[84:85], v[6:7], s[6:7], v[60:61] op_sel_hi:[1,0,1]
	v_pk_fma_f32 v[90:91], v[12:13], s[6:7], v[66:67] op_sel_hi:[1,0,1]
	v_pk_fma_f32 v[88:89], v[10:11], s[6:7], v[64:65] op_sel_hi:[1,0,1]
	v_pk_fma_f32 v[94:95], v[16:17], s[6:7], v[68:69] op_sel_hi:[1,0,1]
	v_pk_fma_f32 v[92:93], v[14:15], s[6:7], v[70:71] op_sel_hi:[1,0,1]
	s_mov_b64 s[0:1], 0

; #define GAS __attribute__((address_space(1)))
; __device__ __forceinline__ float bf2f(unsigned short b) { return __uint_as_float(((unsigned)b) << 16); }
; template <bool GRPB> __device__ __forceinline__ void attn_pass(const float mbK, const float bmax2, const int pass, float* __restrict__ scr, bf16* __restrict__ mixrow, const float lam, const float* __restrict__ gsub, const float one_m_li, ...
;     ...
;   const float cL = __uint_as_float(__builtin_amdgcn_readfirstlane(__float_as_uint(tb2[0]))), cR = __uint_as_float(__builtin_amdgcn_readfirstlane(__float_as_uint(tb2[384])));
;   const int qw = __builtin_amdgcn_readfirstlane(q0seq + wid * 32), qpos = qw + r32;
;   float m_reg, l_reg = 0; bf16x8 qr[4]; f32x16 o[4];
; #pragma unroll
;   for (int d = 0; d < 4; ++d) o[d] = f32x16{};
;   const bf16* Qw = Qb + (long)(wid * 32 + r32) * LDK + hi * 8;
; #pragma unroll
;   for (int d0 = 0; d0 < 4; ++d0) qr[d0] = *(const GAS bf16x8*)(Qw + d0 * 16);
;   { float qs = 0.f;
; #pragma unroll
;     for (int d0 = 0; d0 < 4; ++d0)
; #pragma unroll
;       for (int j = 0; j < 8; ++j) { const float v = bf2f((unsigned short)qr[d0][j]); qs = fmaf(v, v, qs); }
;     { auto rr = __builtin_amdgcn_permlane32_swap(__float_as_uint(qs), __float_as_uint(qs), false, false); qs = __uint_as_float(rr[0]) + __uint_as_float(rr[1]); }
;     m_reg = __builtin_sqrtf(qs) * mbK + bmax2 + 0.25f; }
;     ...
;   GAS f32x4* scr4 = (GAS f32x4*)(scr + (size_t)tid * 64);
;   if (pass == 0) {
; #pragma unroll
;     for (int r4 = 0; r4 < 4; ++r4) { const f32x4 lv = *(const f32x4*)(li_e + 8 * r4 + 4 * hi);
;       const f32x4 rl = (f32x4){__builtin_amdgcn_rcpf(lv[0]), __builtin_amdgcn_rcpf(lv[1]), __builtin_amdgcn_rcpf(lv[2]), __builtin_amdgcn_rcpf(lv[3])};
; #pragma unroll
;       for (int d0 = 0; d0 < 4; ++d0) scr4[d0 * 4 + r4] = (f32x4){o[d0][4 * r4 + 0] * rl[0], o[d0][4 * r4 + 1] * rl[1], o[d0][4 * r4 + 2] * rl[2], o[d0][4 * r4 + 3] * rl[3]}; }
.LBB0_321:
	s_or_b64 exec, exec, s[0:1]
	s_waitcnt lgkmcnt(0)
	v_add_u32_e32 v74, v66, v200
	ds_read_b128 v[66:69], v74
	ds_read_b128 v[70:73], v74 offset:32
	v_ashrrev_i32_e32 v147, 31, v146
	v_lshlrev_b64 v[0:1], 8, v[146:147]
	v_lshl_add_u64 v[0:1], s[40:41], 0, v[0:1]
	s_waitcnt lgkmcnt(1)
	v_rcp_f32_e32 v66, v66
	v_rcp_f32_e32 v67, v67
	v_rcp_f32_e32 v68, v68
	v_rcp_f32_e32 v69, v69
	v_readlane_b32 s0, v254, 39
	v_pk_mul_f32 v[2:3], v[2:3], v[66:67]
	v_mov_b32_e32 v146, v232
	v_pk_mul_f32 v[4:5], v[4:5], v[68:69]
	global_store_dwordx4 v[0:1], v[2:5], off
	v_mov_b32_e32 v201, v144
	s_nop 0
	v_pk_mul_f32 v[2:3], v[18:19], v[66:67]
	v_pk_mul_f32 v[4:5], v[20:21], v[68:69]
	s_waitcnt lgkmcnt(0)
	v_rcp_f32_e32 v18, v70
	v_rcp_f32_e32 v19, v71
	v_rcp_f32_e32 v20, v72
	v_rcp_f32_e32 v21, v73
	global_store_dwordx4 v[0:1], v[2:5], off offset:64
	s_nop 1
	v_pk_mul_f32 v[2:3], v[34:35], v[66:67]
	v_pk_mul_f32 v[4:5], v[36:37], v[68:69]
	global_store_dwordx4 v[0:1], v[2:5], off offset:128
	s_nop 1
	v_pk_mul_f32 v[2:3], v[50:51], v[66:67]
	v_pk_mul_f32 v[4:5], v[52:53], v[68:69]
	global_store_dwordx4 v[0:1], v[2:5], off offset:192
	s_nop 1
	v_pk_mul_f32 v[2:3], v[6:7], v[18:19]
	v_pk_mul_f32 v[4:5], v[8:9], v[20:21]
	global_store_dwordx4 v[0:1], v[2:5], off offset:16
	s_nop 1
	v_pk_mul_f32 v[2:3], v[22:23], v[18:19]
	v_pk_mul_f32 v[4:5], v[24:25], v[20:21]
	global_store_dwordx4 v[0:1], v[2:5], off offset:80
	s_nop 1
	v_pk_mul_f32 v[2:3], v[38:39], v[18:19]
	v_pk_mul_f32 v[4:5], v[40:41], v[20:21]
	global_store_dwordx4 v[0:1], v[2:5], off offset:144
	s_nop 1
	v_pk_mul_f32 v[2:3], v[54:55], v[18:19]
	v_pk_mul_f32 v[4:5], v[56:57], v[20:21]
	global_store_dwordx4 v[0:1], v[2:5], off offset:208
	ds_read_b128 v[2:5], v74 offset:64
	s_waitcnt lgkmcnt(0)
	v_rcp_f32_e32 v6, v2
	v_rcp_f32_e32 v7, v3
	v_rcp_f32_e32 v8, v4
	v_rcp_f32_e32 v9, v5
	v_pk_mul_f32 v[2:3], v[10:11], v[6:7]
	v_mov_b32_e32 v11, v144
	v_pk_mul_f32 v[4:5], v[12:13], v[8:9]
	global_store_dwordx4 v[0:1], v[2:5], off offset:32
	s_nop 1
	v_pk_mul_f32 v[2:3], v[26:27], v[6:7]
	v_pk_mul_f32 v[4:5], v[28:29], v[8:9]
	global_store_dwordx4 v[0:1], v[2:5], off offset:96
	s_nop 1
	v_pk_mul_f32 v[2:3], v[42:43], v[6:7]
	v_pk_mul_f32 v[4:5], v[44:45], v[8:9]
	global_store_dwordx4 v[0:1], v[2:5], off offset:160
	s_nop 1
	v_pk_mul_f32 v[2:3], v[58:59], v[6:7]
	v_pk_mul_f32 v[4:5], v[60:61], v[8:9]
	global_store_dwordx4 v[0:1], v[2:5], off offset:224
	ds_read_b128 v[2:5], v74 offset:96
	s_waitcnt lgkmcnt(0)
	v_rcp_f32_e32 v6, v2
	v_rcp_f32_e32 v7, v3
	v_rcp_f32_e32 v8, v4
	v_rcp_f32_e32 v9, v5
	v_pk_mul_f32 v[2:3], v[14:15], v[6:7]
	v_pk_mul_f32 v[4:5], v[16:17], v[8:9]
	global_store_dwordx4 v[0:1], v[2:5], off offset:48
	s_nop 1
	v_pk_mul_f32 v[2:3], v[30:31], v[6:7]
	v_pk_mul_f32 v[4:5], v[32:33], v[8:9]
	global_store_dwordx4 v[0:1], v[2:5], off offset:112
	s_nop 1
	v_pk_mul_f32 v[2:3], v[46:47], v[6:7]
	v_pk_mul_f32 v[4:5], v[48:49], v[8:9]
	global_store_dwordx4 v[0:1], v[2:5], off offset:176
	s_nop 1
	v_pk_mul_f32 v[2:3], v[62:63], v[6:7]
	v_pk_mul_f32 v[4:5], v[64:65], v[8:9]
	global_store_dwordx4 v[0:1], v[2:5], off offset:240
	v_mov_b32_e32 v0, s0
	ds_read_b32 v0, v0
	v_readlane_b32 s0, v254, 40
	v_bfe_u32 v217, v146, 5, 1
	v_lshlrev_b32_e32 v200, 4, v217
	v_lshlrev_b32_e32 v12, 3, v146
	s_waitcnt lgkmcnt(0)
	v_readfirstlane_b32 s62, v0
	v_mov_b32_e32 v0, s0
	ds_read_b32 v0, v0
	s_movk_i32 s0, 0xffe0
	v_bfe_u32 v5, v12, 5, 2
	v_lshlrev_b32_e32 v6, 4, v146
	v_and_b32_e32 v7, 48, v6
	s_waitcnt lgkmcnt(0)
	v_readfirstlane_b32 s63, v0
	v_ashrrev_i32_e32 v0, 1, v146
	v_and_b32_e32 v215, 0xffffffe0, v0
	v_add_u32_e32 v1, s39, v215
	v_bfi_b32 v0, s0, v0, v146
	v_readfirstlane_b32 s64, v1
	v_ashrrev_i32_e32 v1, 31, v0
	v_lshlrev_b64 v[0:1], 13, v[0:1]
	v_lshl_add_u64 v[0:1], s[52:53], 0, v[0:1]
	v_lshl_add_u64 v[0:1], v[0:1], 0, v[200:201]
	global_load_dwordx4 v[164:167], v[0:1], off offset:128
	global_load_dwordx4 v[160:163], v[0:1], off offset:160
	global_load_dwordx4 v[152:155], v[0:1], off offset:192
	global_load_dwordx4 v[156:159], v[0:1], off offset:224
	v_and_b32_e32 v10, 0x70, v6
	s_barrier
	v_and_b32_e32 v218, 31, v146
	v_add_u32_e32 v147, s64, v218
	s_waitcnt vmcnt(3)
	v_lshlrev_b32_e32 v0, 16, v164
	v_fma_f32 v0, v0, v0, 0
	v_and_b32_e32 v1, 0xffff0000, v164
	v_fmac_f32_e32 v0, v1, v1
	v_lshlrev_b32_e32 v1, 16, v165
	v_fmac_f32_e32 v0, v1, v1
	v_and_b32_e32 v1, 0xffff0000, v165
	v_fmac_f32_e32 v0, v1, v1
	v_lshlrev_b32_e32 v1, 16, v166
	v_fmac_f32_e32 v0, v1, v1
	v_and_b32_e32 v1, 0xffff0000, v166
	v_fmac_f32_e32 v0, v1, v1
	v_lshlrev_b32_e32 v1, 16, v167
	v_fmac_f32_e32 v0, v1, v1
	v_and_b32_e32 v1, 0xffff0000, v167
	v_fmac_f32_e32 v0, v1, v1
	s_waitcnt vmcnt(2)
	v_lshlrev_b32_e32 v1, 16, v160
	v_fmac_f32_e32 v0, v1, v1
	v_and_b32_e32 v1, 0xffff0000, v160
	v_fmac_f32_e32 v0, v1, v1
	v_lshlrev_b32_e32 v1, 16, v161
	v_fmac_f32_e32 v0, v1, v1
	v_and_b32_e32 v1, 0xffff0000, v161
	v_fmac_f32_e32 v0, v1, v1
	v_lshlrev_b32_e32 v1, 16, v162
	v_fmac_f32_e32 v0, v1, v1
	v_and_b32_e32 v1, 0xffff0000, v162
	v_fmac_f32_e32 v0, v1, v1
	v_lshlrev_b32_e32 v1, 16, v163
	v_fmac_f32_e32 v0, v1, v1
	v_and_b32_e32 v1, 0xffff0000, v163
	v_fmac_f32_e32 v0, v1, v1
	s_waitcnt vmcnt(1)
	v_lshlrev_b32_e32 v1, 16, v152
	v_fmac_f32_e32 v0, v1, v1
	v_and_b32_e32 v1, 0xffff0000, v152
	v_fmac_f32_e32 v0, v1, v1
	v_lshlrev_b32_e32 v1, 16, v153
	v_fmac_f32_e32 v0, v1, v1
	v_and_b32_e32 v1, 0xffff0000, v153
	v_fmac_f32_e32 v0, v1, v1
	v_lshlrev_b32_e32 v1, 16, v154
	v_fmac_f32_e32 v0, v1, v1
	v_and_b32_e32 v1, 0xffff0000, v154
	v_fmac_f32_e32 v0, v1, v1
	v_lshlrev_b32_e32 v1, 16, v155
	v_fmac_f32_e32 v0, v1, v1
	v_and_b32_e32 v1, 0xffff0000, v155
	v_fmac_f32_e32 v0, v1, v1
	s_waitcnt vmcnt(0)
; __device__ __forceinline__ float bf2f(unsigned short b) { return __uint_as_float(((unsigned)b) << 16); }
; __device__ __forceinline__ int v_st(int k, int c) { const int kk = (k & ~0xC) | ((k & 4) << 1) | ((k & 8) >> 1); return ((kk >> 3) * 4 + (c >> 5)) * 512 + ((kk & 7) * 32 + (c & 31)) * 2; }
; __device__ __forceinline__ int v_rd_base(int lane) { return ((lane & 3) << 3) | (((lane >> 2) & 3) << 6) | (((lane >> 4) & 1) << 5) | (((lane >> 5) & 1) << 8); }
; #define SLOAD(i, k0) do { sr_[i].vs0 = *(const GAS bf16x8*)(&Vh[(long)((k0) + sr) * LDK + sc]); sr_[i].vs1 = *(const GAS bf16x8*)(&Vh[(long)((k0) + 32 + sr) * LDK + sc]); \
;     sr_[i].ks0 = *(const GAS bf16x8*)(&Kh[(long)((k0) + kr) * LDK + kc]); } while (0)
; #define SWRITE(b, i) do { *(bf16x8*)(V_lds + (b) * SHM_V + vst0) = sr_[i].vs0; *(bf16x8*)(V_lds + (b) * SHM_V + vst1) = sr_[i].vs1; \
;     *(bf16x8*)(K_lds + (b) * SHM_K + kst) = sr_[i].ks0; } while (0)
; template <bool GRPB> __device__ __forceinline__ void attn_pass(const float mbK, const float bmax2, const int pass, float* __restrict__ scr, bf16* __restrict__ mixrow, const float lam, const float* __restrict__ gsub, const float one_m_li, ...
;     ...
;   { float qs = 0.f;
; #pragma unroll
;     for (int d0 = 0; d0 < 4; ++d0)
; #pragma unroll
;       for (int j = 0; j < 8; ++j) { const float v = bf2f((unsigned short)qr[d0][j]); qs = fmaf(v, v, qs); }
;     { auto rr = __builtin_amdgcn_permlane32_swap(__float_as_uint(qs), __float_as_uint(qs), false, false); qs = __uint_as_float(rr[0]) + __uint_as_float(rr[1]); }
;     m_reg = __builtin_sqrtf(qs) * mbK + bmax2 + 0.25f; }
;   const int sr = tid >> 4, sc = (tid & 15) * 8, vst0 = v_st(sr, sc), vst1 = v_st(32 + sr, sc);
;   const int kr = tid >> 3, kc = (tid & 7) * 8, kst = KSWZ64(kr, kc * 2);
;   const int vb0 = (int)(uintptr_t)V_lds + v_rd_base(lane);
;   struct { bf16x8 vs0, vs1, ks0; } sr_[2];
;     ...
;   f32x16 pA0, pA1, pB0, pB1; float mnA, mnB, alA, alB; bf16x8 pa0, pa1, pa2, pa3; constexpr int NT = SEQ / KVBLK;
;   __syncthreads();
;   SLOAD(0, 0); SLOAD(1, KVBLK); asm volatile("s_waitcnt vmcnt(0)" ::: "memory"); SWRITE(0, 0); SWRITE(1, 1);
;   SLOAD(0, 2 * KVBLK); asm volatile("s_waitcnt vmcnt(0)" ::: "memory"); SWRITE(2, 0); __syncthreads();
	v_lshlrev_b32_e32 v1, 16, v156
	v_fmac_f32_e32 v0, v1, v1
	v_and_b32_e32 v1, 0xffff0000, v156
	v_fmac_f32_e32 v0, v1, v1
	v_lshlrev_b32_e32 v1, 16, v157
	v_fmac_f32_e32 v0, v1, v1
	v_and_b32_e32 v1, 0xffff0000, v157
	v_fmac_f32_e32 v0, v1, v1
	v_lshlrev_b32_e32 v1, 16, v158
	v_fmac_f32_e32 v0, v1, v1
	v_and_b32_e32 v1, 0xffff0000, v158
	v_fmac_f32_e32 v0, v1, v1
	v_lshlrev_b32_e32 v1, 16, v159
	v_fmac_f32_e32 v0, v1, v1
	v_and_b32_e32 v1, 0xffff0000, v159
	v_fmac_f32_e32 v0, v1, v1
	v_mov_b32_e32 v1, v0
	s_nop 1
	v_permlane32_swap_b32_e32 v0, v1
	v_add_f32_e32 v0, v0, v1
	v_cmp_gt_f32_e32 vcc, s10, v0
	v_mul_f32_e32 v1, 0x4f800000, v0
	s_nop 0
	v_cndmask_b32_e32 v0, v0, v1, vcc
	v_sqrt_f32_e32 v1, v0
	s_nop 0
	v_add_u32_e32 v2, -1, v1
	v_fma_f32 v3, -v2, v1, v0
	v_cmp_ge_f32_e64 s[0:1], 0, v3
	v_add_u32_e32 v3, 1, v1
	s_nop 0
	v_cndmask_b32_e64 v2, v1, v2, s[0:1]
	v_fma_f32 v1, -v3, v1, v0
	v_cmp_lt_f32_e64 s[0:1], 0, v1
	s_nop 1
	v_cndmask_b32_e64 v1, v2, v3, s[0:1]
	v_mul_f32_e32 v2, 0x37800000, v1
	v_cndmask_b32_e32 v1, v1, v2, vcc
	v_cmp_class_f32_e32 vcc, v0, v198
	v_and_b32_e32 v2, 0x78, v12
	v_lshlrev_b32_e32 v6, 1, v2
	v_cndmask_b32_e32 v0, v1, v0, vcc
	v_fma_f32 v0, v214, v0, s45
	v_add_f32_e32 v64, 0x3e800000, v0
	v_ashrrev_i32_e32 v0, 4, v146
	v_and_b32_e32 v1, 0xfffff0, v0
	v_lshlrev_b32_e32 v3, 1, v0
	v_and_or_b32 v1, v3, 8, v1
	v_lshrrev_b32_e32 v3, 1, v0
	v_lshrrev_b32_e32 v1, 1, v1
	v_and_b32_e32 v4, 3, v0
	v_or_b32_e32 v1, v1, v5
	v_and_or_b32 v3, v3, 4, v4
	v_lshlrev_b32_e32 v1, 9, v1
	v_lshlrev_b32_e32 v3, 6, v3
	v_add_u32_e32 v4, 32, v0
	v_or3_b32 v221, v1, v3, v7
	v_and_b32_e32 v1, 0xfffff0, v4
	v_lshlrev_b32_e32 v8, 1, v4
	v_and_or_b32 v1, v8, 8, v1
	v_lshrrev_b32_e32 v1, 1, v1
	v_or_b32_e32 v1, v1, v5
	v_lshlrev_b32_e32 v1, 9, v1
	v_ashrrev_i32_e32 v8, 3, v146
	v_or3_b32 v222, v1, v3, v7
	v_lshlrev_b32_e32 v1, 7, v8
	v_and_b32_e32 v3, 0x70, v146
	v_bitop3_b32 v223, v10, v1, v3 bitop3:0xde
	v_ashrrev_i32_e32 v1, 31, v0
	v_lshlrev_b64 v[48:49], 13, v[0:1]
	v_lshl_add_u64 v[0:1], s[50:51], 0, v[48:49]
	v_mov_b32_e32 v7, v144
	v_ashrrev_i32_e32 v5, 31, v4
	v_lshl_add_u64 v[26:27], v[0:1], 0, v[6:7]
	v_lshlrev_b64 v[4:5], 13, v[4:5]
	global_load_dwordx4 v[0:3], v[26:27], off offset:2048
	v_lshl_add_u64 v[4:5], s[50:51], 0, v[4:5]
	v_ashrrev_i32_e32 v9, 31, v8
	s_mov_b32 s0, 0x80000
	v_lshl_add_u64 v[4:5], v[4:5], 0, v[6:7]
	v_lshlrev_b64 v[50:51], 13, v[8:9]
	v_add_co_u32_e32 v14, vcc, s0, v26
	global_load_dwordx4 v[4:7], v[4:5], off offset:2048
	v_lshl_add_u64 v[8:9], s[50:51], 0, v[50:51]
	v_addc_co_u32_e32 v15, vcc, 0, v27, vcc
	s_mov_b32 s1, 0xc0000
	v_lshl_add_u64 v[28:29], v[8:9], 0, v[10:11]
	v_add_co_u32_e32 v18, vcc, s1, v26
	global_load_dwordx4 v[8:11], v[28:29], off offset:1152
	s_nop 0
	v_addc_co_u32_e32 v19, vcc, 0, v27, vcc
	global_load_dwordx4 v[14:17], v[14:15], off offset:2048
	v_add_co_u32_e32 v22, vcc, s0, v28
	global_load_dwordx4 v[18:21], v[18:19], off offset:2048
	s_nop 0
	v_addc_co_u32_e32 v23, vcc, 0, v29, vcc
	global_load_dwordx4 v[22:25], v[22:23], off offset:1152
	v_add_u32_e32 v13, 0, v221
	s_mov_b32 s0, 0x100000
	s_waitcnt vmcnt(3)
	v_add_u32_e32 v30, 0, v222
	s_mov_b32 s1, 0x140000
	v_add_u32_e32 v224, 0, v223
	s_waitcnt vmcnt(5)
	ds_write_b128 v13, v[0:3]
	v_add_co_u32_e32 v0, vcc, s0, v26
	s_waitcnt vmcnt(4)
	ds_write_b128 v30, v[4:7]
	v_addc_co_u32_e32 v1, vcc, 0, v27, vcc
	v_add_co_u32_e32 v4, vcc, s1, v26
	s_waitcnt vmcnt(3)
	ds_write_b128 v224, v[8:11] offset:49152
	v_addc_co_u32_e32 v5, vcc, 0, v27, vcc
	v_add_co_u32_e32 v8, vcc, s0, v28
	global_load_dwordx4 v[0:3], v[0:1], off offset:2048
	s_nop 0
	v_addc_co_u32_e32 v9, vcc, 0, v29, vcc
	global_load_dwordx4 v[4:7], v[4:5], off offset:2048
	s_nop 0
	global_load_dwordx4 v[8:11], v[8:9], off offset:1152
	s_waitcnt vmcnt(5)
	ds_write_b128 v13, v[14:17] offset:16384
	s_waitcnt vmcnt(4)
	ds_write_b128 v30, v[18:21] offset:16384
	s_waitcnt vmcnt(3)
	ds_write_b128 v224, v[22:25] offset:57344
	s_waitcnt vmcnt(0)
	s_waitcnt vmcnt(2)
	ds_write_b128 v13, v[0:3] offset:32768
	s_waitcnt vmcnt(1)
	ds_write_b128 v30, v[4:7] offset:32768
	v_add_u32_e32 v0, 0x10000, v224
	s_waitcnt vmcnt(0)
	ds_write_b128 v0, v[8:11]
	v_lshlrev_b32_e32 v8, 7, v218
	v_and_b32_e32 v9, 0x70, v12
	v_or_b32_e32 v10, 32, v200
	v_bitop3_b32 v229, v10, v8, v9 bitop3:0xde
	v_or_b32_e32 v10, 64, v200
	v_bitop3_b32 v231, v10, v8, v9 bitop3:0xde
	v_or_b32_e32 v10, 0x60, v200
	v_bitop3_b32 v226, v200, v8, v9 bitop3:0xde
	v_bitop3_b32 v240, v10, v8, v9 bitop3:0xde
	v_add_u32_e32 v225, 0, v226
	v_add_u32_e32 v227, 0, v229
	v_add_u32_e32 v228, 0, v231
	v_add_u32_e32 v230, 0, v240
	s_waitcnt lgkmcnt(0)
	s_barrier
; #define SBAR() __builtin_amdgcn_sched_barrier(0)
; __device__ __forceinline__ void partialSM(f32x16& p0, f32x16& p1, float& m_reg, float& mn, float& alpha, int kt0, int qpos, int qw, int hi, const float* tb2, float cL, float cR) {
;   mn = m_reg; alpha = 1.f;
;   const int rel_hi = kt0 + 63 - qw, rel_lo = kt0 - (qw + 31);
;   if (rel_hi <= -91 || rel_lo >= 91) {
;     const float cm = ((rel_hi <= -91) ? cL : cR) - m_reg;
; #pragma unroll
;     for (int r = 0; r < 16; ++r) { p0[r] = fmaf(p0[r], C1, cm); p1[r] = fmaf(p1[r], C1, cm); }
;   } else {
;     const float* tp = tb2 + (kt0 - qpos + 192 + 4 * hi);
; #pragma unroll
;     for (int r4 = 0; r4 < 4; ++r4) {
;       float ta[4], tb[4];
; #pragma unroll
;       for (int i = 0; i < 4; ++i) { ta[i] = tp[8 * r4 + i] - m_reg; tb[i] = tp[32 + 8 * r4 + i] - m_reg; }
; #pragma unroll
;       for (int i = 0; i < 4; ++i) { p0[4 * r4 + i] = fmaf(p0[4 * r4 + i], C1, ta[i]); p1[4 * r4 + i] = fmaf(p1[4 * r4 + i], C1, tb[i]); }
; __device__ __forceinline__ void qkt(f32x16& p0, f32x16& p1, const char* Ks, const bf16x8* qr, int r32, int hi) {
;   bf16x8 ka[4], kb[4];
; #pragma unroll
;   for (int d0 = 0; d0 < 4; ++d0) { const int cb = (d0 * 16 + hi * 8) * 2;
;     ka[d0] = *reinterpret_cast<const bf16x8*>(Ks + KSWZ64(r32, cb)); kb[d0] = *reinterpret_cast<const bf16x8*>(Ks + KSWZ64(32 + r32, cb)); }
;   asm volatile("s_waitcnt lgkmcnt(0)" ::: "memory"); SBAR();
;   p0 = f32x16{}; p1 = f32x16{};
; #pragma unroll
;   for (int d0 = 0; d0 < 4; ++d0) {
;     p0 = __builtin_amdgcn_mfma_f32_32x32x16_bf16(ka[d0], qr[d0], p0, 0, 0, 0);
;     p1 = __builtin_amdgcn_mfma_f32_32x32x16_bf16(kb[d0], qr[d0], p1, 0, 0, 0); }
; }
	ds_read_b128 v[0:3], v225 offset:49152
	ds_read_b128 v[4:7], v225 offset:53248
	ds_read_b128 v[32:35], v227 offset:49152
	ds_read_b128 v[36:39], v227 offset:53248
	ds_read_b128 v[40:43], v228 offset:49152
	ds_read_b128 v[44:47], v228 offset:53248
	ds_read_b128 v[52:55], v230 offset:49152
	ds_read_b128 v[56:59], v230 offset:53248
	s_waitcnt lgkmcnt(0)
	s_waitcnt lgkmcnt(7)
	v_mfma_f32_32x32x16_bf16 v[16:31], v[0:3], v[164:167], 0
	s_add_i32 s4, s64, 0xffffff66
	s_mov_b64 s[0:1], -1
	s_cmp_gt_u32 s4, 0xfffffeec
	s_waitcnt lgkmcnt(6)
	v_mfma_f32_32x32x16_bf16 v[0:15], v[4:7], v[164:167], 0
	s_waitcnt lgkmcnt(5)
	v_mfma_f32_32x32x16_bf16 v[16:31], v[32:35], v[160:163], v[16:31]
	s_waitcnt lgkmcnt(4)
	v_mfma_f32_32x32x16_bf16 v[0:15], v[36:39], v[160:163], v[0:15]
	s_waitcnt lgkmcnt(3)
	v_mfma_f32_32x32x16_bf16 v[16:31], v[40:43], v[152:155], v[16:31]
	s_waitcnt lgkmcnt(2)
	v_mfma_f32_32x32x16_bf16 v[0:15], v[44:47], v[152:155], v[0:15]
	s_waitcnt lgkmcnt(1)
	v_mfma_f32_32x32x16_bf16 v[16:31], v[52:55], v[156:159], v[16:31]
	v_lshlrev_b32_e32 v52, 2, v147
	s_waitcnt lgkmcnt(0)
	v_mfma_f32_32x32x16_bf16 v[0:15], v[56:59], v[156:159], v[0:15]
	s_cbranch_scc0 .LBB0_323
	v_sub_u32_e32 v32, 0, v52
	s_mov_b32 s0, 0x12b00
	v_add3_u32 v53, v32, v200, s0
	ds_read2_b32 v[32:33], v53 offset1:1
	ds_read2_b32 v[54:55], v53 offset0:32 offset1:33
	ds_read2_b32 v[56:57], v53 offset0:34 offset1:35
	ds_read2_b32 v[34:35], v53 offset0:2 offset1:3
	ds_read2_b32 v[36:37], v53 offset0:8 offset1:9
	ds_read2_b32 v[58:59], v53 offset0:40 offset1:41
	ds_read2_b32 v[60:61], v53 offset0:42 offset1:43
	ds_read2_b32 v[38:39], v53 offset0:10 offset1:11
	ds_read2_b32 v[40:41], v53 offset0:16 offset1:17
	ds_read2_b32 v[62:63], v53 offset0:48 offset1:49
	ds_read2_b32 v[66:67], v53 offset0:50 offset1:51
	ds_read2_b32 v[42:43], v53 offset0:18 offset1:19
	ds_read2_b32 v[44:45], v53 offset0:24 offset1:25
	ds_read2_b32 v[46:47], v53 offset0:26 offset1:27
	ds_read2_b32 v[68:69], v53 offset0:58 offset1:59
	ds_read2_b32 v[70:71], v53 offset0:56 offset1:57
	s_waitcnt lgkmcnt(3)
	v_sub_f32_e32 v45, v45, v64
	v_sub_f32_e32 v44, v44, v64
	s_waitcnt lgkmcnt(2)
	v_sub_f32_e32 v47, v47, v64
	v_sub_f32_e32 v46, v46, v64
	v_sub_f32_e32 v41, v41, v64
	v_sub_f32_e32 v40, v40, v64
	v_sub_f32_e32 v43, v43, v64
	v_sub_f32_e32 v42, v42, v64
	v_sub_f32_e32 v37, v37, v64
	v_sub_f32_e32 v36, v36, v64
	v_sub_f32_e32 v39, v39, v64
	v_sub_f32_e32 v38, v38, v64
	v_sub_f32_e32 v33, v33, v64
	v_sub_f32_e32 v32, v32, v64
	v_sub_f32_e32 v35, v35, v64
	v_sub_f32_e32 v34, v34, v64
	s_waitcnt lgkmcnt(0)
	v_sub_f32_e32 v71, v71, v64
	v_sub_f32_e32 v70, v70, v64
	v_sub_f32_e32 v69, v69, v64
	v_sub_f32_e32 v68, v68, v64
	v_sub_f32_e32 v63, v63, v64
	v_sub_f32_e32 v62, v62, v64
	v_sub_f32_e32 v67, v67, v64
	v_sub_f32_e32 v66, v66, v64
	v_sub_f32_e32 v59, v59, v64
	v_sub_f32_e32 v58, v58, v64
	v_sub_f32_e32 v61, v61, v64
	v_sub_f32_e32 v60, v60, v64
	v_sub_f32_e32 v55, v55, v64
	v_sub_f32_e32 v54, v54, v64
	v_sub_f32_e32 v57, v57, v64
	v_sub_f32_e32 v56, v56, v64
	v_pk_fma_f32 v[34:35], v[18:19], s[6:7], v[34:35] op_sel_hi:[1,0,1]
	v_pk_fma_f32 v[32:33], v[16:17], s[6:7], v[32:33] op_sel_hi:[1,0,1]
	v_pk_fma_f32 v[38:39], v[22:23], s[6:7], v[38:39] op_sel_hi:[1,0,1]
	v_pk_fma_f32 v[36:37], v[20:21], s[6:7], v[36:37] op_sel_hi:[1,0,1]
	v_pk_fma_f32 v[42:43], v[26:27], s[6:7], v[42:43] op_sel_hi:[1,0,1]
	v_pk_fma_f32 v[40:41], v[24:25], s[6:7], v[40:41] op_sel_hi:[1,0,1]
	v_pk_fma_f32 v[46:47], v[30:31], s[6:7], v[46:47] op_sel_hi:[1,0,1]
	v_pk_fma_f32 v[44:45], v[28:29], s[6:7], v[44:45] op_sel_hi:[1,0,1]
	v_pk_fma_f32 v[82:83], v[2:3], s[6:7], v[56:57] op_sel_hi:[1,0,1]
	v_pk_fma_f32 v[80:81], v[0:1], s[6:7], v[54:55] op_sel_hi:[1,0,1]
	v_pk_fma_f32 v[86:87], v[6:7], s[6:7], v[60:61] op_sel_hi:[1,0,1]
	v_pk_fma_f32 v[84:85], v[4:5], s[6:7], v[58:59] op_sel_hi:[1,0,1]
	v_pk_fma_f32 v[90:91], v[10:11], s[6:7], v[66:67] op_sel_hi:[1,0,1]
	v_pk_fma_f32 v[88:89], v[8:9], s[6:7], v[62:63] op_sel_hi:[1,0,1]
	v_pk_fma_f32 v[94:95], v[14:15], s[6:7], v[68:69] op_sel_hi:[1,0,1]
	v_pk_fma_f32 v[92:93], v[12:13], s[6:7], v[70:71] op_sel_hi:[1,0,1]
	s_mov_b64 s[0:1], 0

; #define GAS __attribute__((address_space(1)))
; __device__ __forceinline__ float bf2f(unsigned short b) { return __uint_as_float(((unsigned)b) << 16); }
; __device__ __forceinline__ int v_st(int k, int c) { const int kk = (k & ~0xC) | ((k & 4) << 1) | ((k & 8) >> 1); return ((kk >> 3) * 4 + (c >> 5)) * 512 + ((kk & 7) * 32 + (c & 31)) * 2; }
; __device__ __forceinline__ int v_rd_base(int lane) { return ((lane & 3) << 3) | (((lane >> 2) & 3) << 6) | (((lane >> 4) & 1) << 5) | (((lane >> 5) & 1) << 8); }
; template <bool GRPB> __device__ __forceinline__ void attn_pass(const float mbK, const float bmax2, const int pass, float* __restrict__ scr, bf16* __restrict__ mixrow, const float lam, const float* __restrict__ gsub, const float one_m_li, ...
;     ...
;   const float cL = __uint_as_float(__builtin_amdgcn_readfirstlane(__float_as_uint(tb2[0]))), cR = __uint_as_float(__builtin_amdgcn_readfirstlane(__float_as_uint(tb2[384])));
;   const int qw = __builtin_amdgcn_readfirstlane(q0seq + wid * 32), qpos = qw + r32;
;   float m_reg, l_reg = 0; bf16x8 qr[4]; f32x16 o[4];
; #pragma unroll
;   for (int d = 0; d < 4; ++d) o[d] = f32x16{};
;   const bf16* Qw = Qb + (long)(wid * 32 + r32) * LDK + hi * 8;
; #pragma unroll
;   for (int d0 = 0; d0 < 4; ++d0) qr[d0] = *(const GAS bf16x8*)(Qw + d0 * 16);
;   { float qs = 0.f;
; #pragma unroll
;     for (int d0 = 0; d0 < 4; ++d0)
; #pragma unroll
;       for (int j = 0; j < 8; ++j) { const float v = bf2f((unsigned short)qr[d0][j]); qs = fmaf(v, v, qs); }
;     { auto rr = __builtin_amdgcn_permlane32_swap(__float_as_uint(qs), __float_as_uint(qs), false, false); qs = __uint_as_float(rr[0]) + __uint_as_float(rr[1]); }
;     m_reg = __builtin_sqrtf(qs) * mbK + bmax2 + 0.25f; }
;   const int sr = tid >> 4, sc = (tid & 15) * 8, vst0 = v_st(sr, sc), vst1 = v_st(32 + sr, sc);
;   const int kr = tid >> 3, kc = (tid & 7) * 8, kst = KSWZ64(kr, kc * 2);
;   const int vb0 = (int)(uintptr_t)V_lds + v_rd_base(lane);
;   struct { bf16x8 vs0, vs1, ks0; } sr_[2];
;     ...
;   f32x16 pA0, pA1, pB0, pB1; float mnA, mnB, alA, alB; bf16x8 pa0, pa1, pa2, pa3; constexpr int NT = SEQ / KVBLK;
;   __syncthreads();
;   SLOAD(0, 0); SLOAD(1, KVBLK); asm volatile("s_waitcnt vmcnt(0)" ::: "memory"); SWRITE(0, 0); SWRITE(1, 1);
;   SLOAD(0, 2 * KVBLK); asm volatile("s_waitcnt vmcnt(0)" ::: "memory"); SWRITE(2, 0); __syncthreads();
.LBB0_347:
	s_and_b64 vcc, exec, s[0:1]
	s_cbranch_vccz .LBB0_249
	v_readlane_b32 s0, v254, 39
	v_mov_b32_e32 v146, v232
	v_mov_b32_e32 v181, v144
	v_mov_b32_e32 v0, s0
	ds_read_b32 v0, v0
	v_readlane_b32 s0, v254, 40
	v_lshrrev_b32_e32 v2, 1, v146
	v_and_b32_e32 v180, 16, v2
	v_lshlrev_b32_e32 v8, 4, v146
	s_waitcnt lgkmcnt(0)
	v_readfirstlane_b32 s54, v0
	v_mov_b32_e32 v0, s0
	ds_read_b32 v0, v0
	s_movk_i32 s0, 0xffe0
	v_and_b32_e32 v9, 48, v8
	v_ashrrev_i32_e32 v12, 3, v146
	v_ashrrev_i32_e32 v13, 31, v12
	s_waitcnt lgkmcnt(0)
	v_readfirstlane_b32 s55, v0
	v_ashrrev_i32_e32 v0, 1, v146
	v_and_b32_e32 v1, 0xffffffe0, v0
	v_add_u32_e32 v1, s39, v1
	v_bfi_b32 v0, s0, v0, v146
	v_readfirstlane_b32 s60, v1
	v_ashrrev_i32_e32 v1, 31, v0
	v_lshlrev_b64 v[0:1], 13, v[0:1]
	v_lshl_add_u64 v[0:1], s[52:53], 0, v[0:1]
	v_lshl_add_u64 v[0:1], v[0:1], 0, v[180:181]
	global_load_dwordx4 v[164:167], v[0:1], off
	global_load_dwordx4 v[160:163], v[0:1], off offset:32
	global_load_dwordx4 v[156:159], v[0:1], off offset:64
	global_load_dwordx4 v[152:155], v[0:1], off offset:96
	s_barrier
	v_lshlrev_b64 v[52:53], 13, v[12:13]
	v_mov_b32_e32 v11, v144
	v_and_b32_e32 v147, 31, v146
	v_add_u32_e32 v190, s60, v147
	s_waitcnt vmcnt(3)
	v_lshlrev_b32_e32 v0, 16, v164
	v_fma_f32 v0, v0, v0, 0
	v_and_b32_e32 v1, 0xffff0000, v164
	v_fmac_f32_e32 v0, v1, v1
	v_lshlrev_b32_e32 v1, 16, v165
	v_fmac_f32_e32 v0, v1, v1
	v_and_b32_e32 v1, 0xffff0000, v165
	v_fmac_f32_e32 v0, v1, v1
	v_lshlrev_b32_e32 v1, 16, v166
	v_fmac_f32_e32 v0, v1, v1
	v_and_b32_e32 v1, 0xffff0000, v166
	v_fmac_f32_e32 v0, v1, v1
	v_lshlrev_b32_e32 v1, 16, v167
	v_fmac_f32_e32 v0, v1, v1
	v_and_b32_e32 v1, 0xffff0000, v167
	v_fmac_f32_e32 v0, v1, v1
	s_waitcnt vmcnt(2)
	v_lshlrev_b32_e32 v1, 16, v160
	v_fmac_f32_e32 v0, v1, v1
	v_and_b32_e32 v1, 0xffff0000, v160
	v_fmac_f32_e32 v0, v1, v1
	v_lshlrev_b32_e32 v1, 16, v161
	v_fmac_f32_e32 v0, v1, v1
	v_and_b32_e32 v1, 0xffff0000, v161
	v_fmac_f32_e32 v0, v1, v1
	v_lshlrev_b32_e32 v1, 16, v162
	v_fmac_f32_e32 v0, v1, v1
	v_and_b32_e32 v1, 0xffff0000, v162
	v_fmac_f32_e32 v0, v1, v1
	v_lshlrev_b32_e32 v1, 16, v163
	v_fmac_f32_e32 v0, v1, v1
	v_and_b32_e32 v1, 0xffff0000, v163
	v_fmac_f32_e32 v0, v1, v1
	s_waitcnt vmcnt(1)
	v_lshlrev_b32_e32 v1, 16, v156
	v_fmac_f32_e32 v0, v1, v1
	v_and_b32_e32 v1, 0xffff0000, v156
	v_fmac_f32_e32 v0, v1, v1
	v_lshlrev_b32_e32 v1, 16, v157
	v_fmac_f32_e32 v0, v1, v1
	v_and_b32_e32 v1, 0xffff0000, v157
	v_fmac_f32_e32 v0, v1, v1
	v_lshlrev_b32_e32 v1, 16, v158
	v_fmac_f32_e32 v0, v1, v1
	v_and_b32_e32 v1, 0xffff0000, v158
	v_fmac_f32_e32 v0, v1, v1
	v_lshlrev_b32_e32 v1, 16, v159
	v_fmac_f32_e32 v0, v1, v1
	v_and_b32_e32 v1, 0xffff0000, v159
	v_fmac_f32_e32 v0, v1, v1
	s_waitcnt vmcnt(0)
	v_lshlrev_b32_e32 v1, 16, v152
	v_fmac_f32_e32 v0, v1, v1
	v_and_b32_e32 v1, 0xffff0000, v152
	v_fmac_f32_e32 v0, v1, v1
	v_lshlrev_b32_e32 v1, 16, v153
	v_fmac_f32_e32 v0, v1, v1
	v_and_b32_e32 v1, 0xffff0000, v153
	v_fmac_f32_e32 v0, v1, v1
	v_lshlrev_b32_e32 v1, 16, v154
	v_fmac_f32_e32 v0, v1, v1
	v_and_b32_e32 v1, 0xffff0000, v154
	v_fmac_f32_e32 v0, v1, v1
	v_lshlrev_b32_e32 v1, 16, v155
	v_fmac_f32_e32 v0, v1, v1
	v_and_b32_e32 v1, 0xffff0000, v155
	v_fmac_f32_e32 v0, v1, v1
	v_mov_b32_e32 v1, v0
	s_nop 1
	v_permlane32_swap_b32_e32 v0, v1
	v_add_f32_e32 v0, v0, v1
	v_cmp_gt_f32_e32 vcc, s10, v0
	v_mul_f32_e32 v1, 0x4f800000, v0
	s_nop 0
	v_cndmask_b32_e32 v0, v0, v1, vcc
	v_sqrt_f32_e32 v1, v0
	s_nop 0
	v_add_u32_e32 v2, -1, v1
	v_fma_f32 v3, -v2, v1, v0
	v_cmp_ge_f32_e64 s[0:1], 0, v3
	v_add_u32_e32 v3, 1, v1
	s_nop 0
	v_cndmask_b32_e64 v2, v1, v2, s[0:1]
	v_fma_f32 v1, -v3, v1, v0
	v_cmp_lt_f32_e64 s[0:1], 0, v1
	s_nop 1
	v_cndmask_b32_e64 v1, v2, v3, s[0:1]
	v_mul_f32_e32 v2, 0x37800000, v1
	v_cndmask_b32_e32 v1, v1, v2, vcc
	v_ashrrev_i32_e32 v2, 4, v146
	v_cmp_class_f32_e32 vcc, v0, v198
	v_and_b32_e32 v3, 0xfffff0, v2
	v_lshlrev_b32_e32 v5, 1, v2
	v_cndmask_b32_e32 v0, v1, v0, vcc
	v_lshlrev_b32_e32 v1, 3, v146
	v_and_or_b32 v3, v5, 8, v3
	v_lshrrev_b32_e32 v5, 1, v2
	v_lshrrev_b32_e32 v3, 1, v3
	v_bfe_u32 v7, v1, 5, 2
	v_and_b32_e32 v6, 3, v2
	v_or_b32_e32 v3, v3, v7
	v_and_or_b32 v5, v5, 4, v6
	v_lshlrev_b32_e32 v3, 9, v3
	v_lshlrev_b32_e32 v5, 6, v5
	v_add_u32_e32 v6, 32, v2
	v_or3_b32 v181, v3, v5, v9
	v_and_b32_e32 v3, 0xfffff0, v6
	v_lshlrev_b32_e32 v10, 1, v6
	v_and_or_b32 v3, v10, 8, v3
	v_lshrrev_b32_e32 v3, 1, v3
	v_or_b32_e32 v3, v3, v7
	v_lshlrev_b32_e32 v3, 9, v3
	v_or3_b32 v191, v3, v5, v9
	v_lshlrev_b32_e32 v3, 7, v12
	v_and_b32_e32 v10, 0x70, v8
	v_and_b32_e32 v5, 0x70, v146
	v_bitop3_b32 v192, v10, v3, v5 bitop3:0xde
	v_ashrrev_i32_e32 v3, 31, v2
	v_and_b32_e32 v4, 0x78, v1
	v_lshlrev_b64 v[50:51], 13, v[2:3]
	v_lshl_add_u64 v[2:3], s[50:51], 0, v[50:51]
	v_lshlrev_b32_e32 v8, 1, v4
	v_mov_b32_e32 v9, v144
	v_ashrrev_i32_e32 v7, 31, v6
	v_lshl_add_u64 v[18:19], v[2:3], 0, v[8:9]
	v_lshlrev_b64 v[6:7], 13, v[6:7]
	global_load_dwordx4 v[2:5], v[18:19], off offset:2048
	v_lshl_add_u64 v[6:7], s[50:51], 0, v[6:7]
	s_mov_b32 s0, 0x80000
	v_lshl_add_u64 v[6:7], v[6:7], 0, v[8:9]
	v_add_co_u32_e32 v14, vcc, s0, v18
	global_load_dwordx4 v[6:9], v[6:7], off offset:2048
	v_lshl_add_u64 v[12:13], s[50:51], 0, v[52:53]
	v_addc_co_u32_e32 v15, vcc, 0, v19, vcc
	s_mov_b32 s1, 0xc0000
	v_lshl_add_u64 v[20:21], v[12:13], 0, v[10:11]
	v_add_co_u32_e32 v22, vcc, s1, v18
	global_load_dwordx4 v[10:13], v[20:21], off offset:1024
	s_nop 0
	v_addc_co_u32_e32 v23, vcc, 0, v19, vcc
	global_load_dwordx4 v[14:17], v[14:15], off offset:2048
	v_add_co_u32_e32 v26, vcc, s0, v20
	global_load_dwordx4 v[22:25], v[22:23], off offset:2048
	s_nop 0
	v_addc_co_u32_e32 v27, vcc, 0, v21, vcc
	global_load_dwordx4 v[26:29], v[26:27], off offset:1024
	v_add_u32_e32 v30, 0, v181
	s_mov_b32 s0, 0x100000
	s_waitcnt vmcnt(3)
; #define SBAR() __builtin_amdgcn_sched_barrier(0)
; __device__ __forceinline__ void partialSM(f32x16& p0, f32x16& p1, float& m_reg, float& mn, float& alpha, int kt0, int qpos, int qw, int hi, const float* tb2, float cL, float cR) {
;   mn = m_reg; alpha = 1.f;
;   const int rel_hi = kt0 + 63 - qw, rel_lo = kt0 - (qw + 31);
;   if (rel_hi <= -91 || rel_lo >= 91) {
;     const float cm = ((rel_hi <= -91) ? cL : cR) - m_reg;
; #pragma unroll
;     for (int r = 0; r < 16; ++r) { p0[r] = fmaf(p0[r], C1, cm); p1[r] = fmaf(p1[r], C1, cm); }
;   } else {
;     const float* tp = tb2 + (kt0 - qpos + 192 + 4 * hi);
; #pragma unroll
;     for (int r4 = 0; r4 < 4; ++r4) {
;       float ta[4], tb[4];
; #pragma unroll
;       for (int i = 0; i < 4; ++i) { ta[i] = tp[8 * r4 + i] - m_reg; tb[i] = tp[32 + 8 * r4 + i] - m_reg; }
; #pragma unroll
;       for (int i = 0; i < 4; ++i) { p0[4 * r4 + i] = fmaf(p0[4 * r4 + i], C1, ta[i]); p1[4 * r4 + i] = fmaf(p1[4 * r4 + i], C1, tb[i]); }
; __device__ __forceinline__ void qkt(f32x16& p0, f32x16& p1, const char* Ks, const bf16x8* qr, int r32, int hi) {
;   bf16x8 ka[4], kb[4];
; #pragma unroll
;   for (int d0 = 0; d0 < 4; ++d0) { const int cb = (d0 * 16 + hi * 8) * 2;
;     ka[d0] = *reinterpret_cast<const bf16x8*>(Ks + KSWZ64(r32, cb)); kb[d0] = *reinterpret_cast<const bf16x8*>(Ks + KSWZ64(32 + r32, cb)); }
;   asm volatile("s_waitcnt lgkmcnt(0)" ::: "memory"); SBAR();
;   p0 = f32x16{}; p1 = f32x16{};
; #pragma unroll
;   for (int d0 = 0; d0 < 4; ++d0) {
;     p0 = __builtin_amdgcn_mfma_f32_32x32x16_bf16(ka[d0], qr[d0], p0, 0, 0, 0);
;     p1 = __builtin_amdgcn_mfma_f32_32x32x16_bf16(kb[d0], qr[d0], p1, 0, 0, 0); }
; }
	v_add_u32_e32 v31, 0, v191
	s_mov_b32 s1, 0x140000
	v_add_u32_e32 v200, 0, v192
	v_and_b32_e32 v1, 0x70, v1
	v_fma_f32 v0, v216, v0, s45
	v_add_f32_e32 v0, 0x3e800000, v0
	s_waitcnt vmcnt(5)
	ds_write_b128 v30, v[2:5]
	v_add_co_u32_e32 v2, vcc, s0, v18
	s_waitcnt vmcnt(4)
	ds_write_b128 v31, v[6:9]
	v_addc_co_u32_e32 v3, vcc, 0, v19, vcc
	v_add_co_u32_e32 v6, vcc, s1, v18
	s_waitcnt vmcnt(3)
	ds_write_b128 v200, v[10:13] offset:49152
	v_addc_co_u32_e32 v7, vcc, 0, v19, vcc
	v_add_co_u32_e32 v10, vcc, s0, v20
	global_load_dwordx4 v[2:5], v[2:3], off offset:2048
	s_nop 0
	v_addc_co_u32_e32 v11, vcc, 0, v21, vcc
	global_load_dwordx4 v[6:9], v[6:7], off offset:2048
	s_nop 0
	global_load_dwordx4 v[10:13], v[10:11], off offset:1024
	s_waitcnt vmcnt(5)
	ds_write_b128 v30, v[14:17] offset:16384
	s_waitcnt vmcnt(4)
	ds_write_b128 v31, v[22:25] offset:16384
	s_waitcnt vmcnt(3)
	ds_write_b128 v200, v[26:29] offset:57344
	s_waitcnt vmcnt(0)
	s_waitcnt vmcnt(2)
	ds_write_b128 v30, v[2:5] offset:32768
	s_waitcnt vmcnt(1)
	ds_write_b128 v31, v[6:9] offset:32768
	v_add_u32_e32 v2, 0x10000, v200
	s_waitcnt vmcnt(0)
	ds_write_b128 v2, v[10:13]
	v_lshlrev_b32_e32 v10, 7, v147
	v_or_b32_e32 v11, 32, v180
	v_bitop3_b32 v205, v11, v10, v1 bitop3:0xde
	v_or_b32_e32 v11, 64, v180
	v_bitop3_b32 v207, v11, v10, v1 bitop3:0xde
	v_or_b32_e32 v11, 0x60, v180
	v_bitop3_b32 v202, v180, v10, v1 bitop3:0xde
	v_bitop3_b32 v208, v11, v10, v1 bitop3:0xde
	v_add_u32_e32 v201, 0, v202
	v_add_u32_e32 v203, 0, v205
	v_add_u32_e32 v204, 0, v207
	v_add_u32_e32 v206, 0, v208
	s_waitcnt lgkmcnt(0)
	s_barrier
	ds_read_b128 v[2:5], v201 offset:49152
	ds_read_b128 v[6:9], v201 offset:53248
	ds_read_b128 v[34:37], v203 offset:49152
	ds_read_b128 v[38:41], v203 offset:53248
	ds_read_b128 v[42:45], v204 offset:49152
	ds_read_b128 v[46:49], v204 offset:53248
	ds_read_b128 v[54:57], v206 offset:49152
	ds_read_b128 v[58:61], v206 offset:53248
	s_waitcnt lgkmcnt(0)
	s_waitcnt lgkmcnt(7)
	v_mfma_f32_32x32x16_bf16 v[18:33], v[2:5], v[164:167], 0
	s_add_i32 s2, s60, 0xffffff66
	s_mov_b64 s[0:1], -1
	s_cmp_gt_u32 s2, 0xfffffeec
	s_waitcnt lgkmcnt(6)
	v_mfma_f32_32x32x16_bf16 v[2:17], v[6:9], v[164:167], 0
	s_waitcnt lgkmcnt(5)
	v_mfma_f32_32x32x16_bf16 v[18:33], v[34:37], v[160:163], v[18:33]
	s_waitcnt lgkmcnt(4)
	v_mfma_f32_32x32x16_bf16 v[2:17], v[38:41], v[160:163], v[2:17]
	s_waitcnt lgkmcnt(3)
	v_mfma_f32_32x32x16_bf16 v[18:33], v[42:45], v[156:159], v[18:33]
	s_waitcnt lgkmcnt(2)
	v_mfma_f32_32x32x16_bf16 v[2:17], v[46:49], v[156:159], v[2:17]
	s_waitcnt lgkmcnt(1)
	v_mfma_f32_32x32x16_bf16 v[18:33], v[54:57], v[152:155], v[18:33]
	v_lshlrev_b32_e32 v54, 2, v190
	s_waitcnt lgkmcnt(0)
	v_mfma_f32_32x32x16_bf16 v[2:17], v[58:61], v[152:155], v[2:17]
	s_cbranch_scc0 .LBB0_350
	v_sub_u32_e32 v1, 0, v54
	s_mov_b32 s0, 0x12b00
	v_add3_u32 v1, v1, v180, s0
	ds_read2_b32 v[34:35], v1 offset1:1
	ds_read2_b32 v[56:57], v1 offset0:32 offset1:33
	ds_read2_b32 v[58:59], v1 offset0:34 offset1:35
	ds_read2_b32 v[36:37], v1 offset0:2 offset1:3
	ds_read2_b32 v[38:39], v1 offset0:8 offset1:9
	ds_read2_b32 v[60:61], v1 offset0:40 offset1:41
	ds_read2_b32 v[62:63], v1 offset0:42 offset1:43
	ds_read2_b32 v[40:41], v1 offset0:10 offset1:11
	ds_read2_b32 v[42:43], v1 offset0:16 offset1:17
	ds_read2_b32 v[64:65], v1 offset0:48 offset1:49
	ds_read2_b32 v[66:67], v1 offset0:50 offset1:51
	ds_read2_b32 v[44:45], v1 offset0:18 offset1:19
	ds_read2_b32 v[46:47], v1 offset0:24 offset1:25
	ds_read2_b32 v[48:49], v1 offset0:26 offset1:27
	ds_read2_b32 v[68:69], v1 offset0:58 offset1:59
	ds_read2_b32 v[70:71], v1 offset0:56 offset1:57
	s_waitcnt lgkmcnt(3)
	v_sub_f32_e32 v47, v47, v0
	v_sub_f32_e32 v46, v46, v0
	s_waitcnt lgkmcnt(2)
	v_sub_f32_e32 v49, v49, v0
	v_sub_f32_e32 v48, v48, v0
	v_sub_f32_e32 v43, v43, v0
	v_sub_f32_e32 v42, v42, v0
	v_sub_f32_e32 v45, v45, v0
	v_sub_f32_e32 v44, v44, v0
	v_sub_f32_e32 v39, v39, v0
	v_sub_f32_e32 v38, v38, v0
	v_sub_f32_e32 v41, v41, v0
	v_sub_f32_e32 v40, v40, v0
	v_sub_f32_e32 v35, v35, v0
	v_sub_f32_e32 v34, v34, v0
	v_sub_f32_e32 v37, v37, v0
	v_sub_f32_e32 v36, v36, v0
	s_waitcnt lgkmcnt(0)
	v_sub_f32_e32 v71, v71, v0
	v_sub_f32_e32 v70, v70, v0
	v_sub_f32_e32 v69, v69, v0
	v_sub_f32_e32 v68, v68, v0
	v_sub_f32_e32 v65, v65, v0
	v_sub_f32_e32 v64, v64, v0
	v_sub_f32_e32 v67, v67, v0
	v_sub_f32_e32 v66, v66, v0
	v_sub_f32_e32 v61, v61, v0
	v_sub_f32_e32 v60, v60, v0
	v_sub_f32_e32 v63, v63, v0
	v_sub_f32_e32 v62, v62, v0
	v_sub_f32_e32 v57, v57, v0
	v_sub_f32_e32 v56, v56, v0
	v_sub_f32_e32 v59, v59, v0
	v_sub_f32_e32 v58, v58, v0
	v_pk_fma_f32 v[36:37], v[20:21], s[6:7], v[36:37] op_sel_hi:[1,0,1]
	v_pk_fma_f32 v[34:35], v[18:19], s[6:7], v[34:35] op_sel_hi:[1,0,1]
	v_pk_fma_f32 v[40:41], v[24:25], s[6:7], v[40:41] op_sel_hi:[1,0,1]
	v_pk_fma_f32 v[38:39], v[22:23], s[6:7], v[38:39] op_sel_hi:[1,0,1]
	v_pk_fma_f32 v[44:45], v[28:29], s[6:7], v[44:45] op_sel_hi:[1,0,1]
	v_pk_fma_f32 v[42:43], v[26:27], s[6:7], v[42:43] op_sel_hi:[1,0,1]
	v_pk_fma_f32 v[48:49], v[32:33], s[6:7], v[48:49] op_sel_hi:[1,0,1]
	v_pk_fma_f32 v[46:47], v[30:31], s[6:7], v[46:47] op_sel_hi:[1,0,1]
	v_pk_fma_f32 v[82:83], v[4:5], s[6:7], v[58:59] op_sel_hi:[1,0,1]
	v_pk_fma_f32 v[80:81], v[2:3], s[6:7], v[56:57] op_sel_hi:[1,0,1]
	v_pk_fma_f32 v[86:87], v[8:9], s[6:7], v[62:63] op_sel_hi:[1,0,1]
	v_pk_fma_f32 v[84:85], v[6:7], s[6:7], v[60:61] op_sel_hi:[1,0,1]
	v_pk_fma_f32 v[90:91], v[12:13], s[6:7], v[66:67] op_sel_hi:[1,0,1]
	v_pk_fma_f32 v[88:89], v[10:11], s[6:7], v[64:65] op_sel_hi:[1,0,1]
	v_pk_fma_f32 v[94:95], v[16:17], s[6:7], v[68:69] op_sel_hi:[1,0,1]
	v_pk_fma_f32 v[92:93], v[14:15], s[6:7], v[70:71] op_sel_hi:[1,0,1]
	s_mov_b64 s[0:1], 0
